# phase A weight-transpose tiles processed in pairs (16 row loads in flight), static loop walks pair indices
# speedup vs baseline: 1.0027x; 1.0015x over previous
; DI void xpose_tile(int wv0, PP p, int jt, unsigned char* smem) {
;     ...
;   {
;     const int n = tid >> 3, kc = tid & 7;
;     uint4 o;
;     o.x = pk2(tile[(kc * 8 + 0) * 65 + n], tile[(kc * 8 + 1) * 65 + n]);
;     o.y = pk2(tile[(kc * 8 + 2) * 65 + n], tile[(kc * 8 + 3) * 65 + n]);
;     o.z = pk2(tile[(kc * 8 + 4) * 65 + n], tile[(kc * 8 + 5) * 65 + n]);
;     o.w = pk2(tile[(kc * 8 + 6) * 65 + n], tile[(kc * 8 + 7) * 65 + n]);
;     const int drow = rowil < 0 ? (n0 + n) : (((n0 + n) >> 7) * 256 + ((n0 + n) & 127) + rowil);
;     *(uint4*)(dst + (size_t)drow * K + k0 + kc * 8) = o;
;   }
;   __syncthreads();
; DI void phaseA(int wv0, PP p, unsigned char* smem) {
;     ...
;   for (int jt = blockIdx.x; jt < NXT_A + 32 + 32; jt += gridDim.x) {
;     if (jt < NXT_A) {
;       xpose_tile(wv0, p, jt, smem);
.LBB0_65:
	s_or_b64 exec, exec, s[20:21]
	v_lshlrev_b32_e32 v10, 3, v12
	v_ashrrev_i32_e32 v6, 3, v12
	v_and_b32_e32 v32, 56, v10
	v_mul_u32_u24_e32 v10, 0x104, v32
	v_lshlrev_b32_e32 v11, 2, v6
	v_add3_u32 v12, 32, v10, v11
	v_add_u32_e32 v13, 0x400, v12
	v_add_u32_e32 v232, 0x4100, v12
	v_add_u32_e32 v233, 0x4500, v12
	s_waitcnt lgkmcnt(0)
	s_barrier
	ds_read2_b32 v[224:225], v233 offset0:134 offset1:199
	ds_read2_b32 v[226:227], v233 offset0:4 offset1:69
	ds_read2_b32 v[228:229], v232 offset0:130 offset1:195
	ds_read2_b32 v[230:231], v232 offset1:65
	ds_read2_b32 v[10:11], v13 offset0:134 offset1:199
	ds_read2_b32 v[14:15], v13 offset0:4 offset1:69
	ds_read2_b32 v[16:17], v12 offset0:130 offset1:195
	ds_read2_b32 v[30:31], v12 offset1:65
	v_add_u32_e32 v6, s54, v6
	s_waitcnt lgkmcnt(3)
	v_cvt_pk_bf16_f32 v13, v10, v11
	s_waitcnt lgkmcnt(2)
	v_cvt_pk_bf16_f32 v12, v14, v15
	v_mad_u64_u32 v[14:15], s[8:9], v6, s22, 0
	s_waitcnt lgkmcnt(1)
	v_cvt_pk_bf16_f32 v11, v16, v17
	v_ashrrev_i32_e32 v16, 31, v6
	v_mov_b32_e32 v6, v15
	v_mad_u64_u32 v[16:17], s[8:9], v16, s22, v[6:7]
	v_mov_b32_e32 v15, v16
	v_lshl_add_u64 v[14:15], v[14:15], 1, s[10:11]
	s_ashr_i32 s17, s16, 31
	v_lshl_add_u64 v[14:15], s[16:17], 1, v[14:15]
	v_lshlrev_b32_e32 v6, 1, v32
	s_waitcnt lgkmcnt(0)
	v_cvt_pk_bf16_f32 v10, v30, v31
	v_lshl_add_u64 v[14:15], v[14:15], 0, v[6:7]
	global_store_dwordx4 v[14:15], v[10:13], off
	v_cvt_pk_bf16_f32 v236, v230, v231
	v_cvt_pk_bf16_f32 v237, v228, v229
	v_cvt_pk_bf16_f32 v238, v226, v227
	v_cvt_pk_bf16_f32 v239, v224, v225
	global_store_dwordx4 v[14:15], v[236:239], off offset:128
	s_barrier
.LBB0_66:
	s_load_dword s8, s[52:53], 0x0
	s_waitcnt lgkmcnt(0)
	s_add_i32 s87, s8, s32
	s_cmpk_gt_i32 s87, 0x2cf
	s_cbranch_scc1 .LBB0_126
.LBB0_67:
	s_mov_b32 s32, s87
	s_cmpk_lt_u32 s32, 0x290
	s_cbranch_scc0 .Lmy_a_single
	s_lshl_b32 s87, s32, 1
	s_branch .Lmy_a_idx
.Lmy_a_single:
	s_add_i32 s87, s32, 0x290

; DI void xpose_tile(int wv0, PP p, int jt, unsigned char* smem) {
;     ...
;   for (int kk = ty; kk < 64; kk += 8) {
;     float val = 0.f;
;     if (sc >= 0) val = src[(size_t)(k0 + kk) * Nsrc + sc];
;     if (scl) val *= scl[k0 + kk];
;     tile[kk * 65 + tx] = val;
;   }
.LBB0_120:
	s_mul_i32 s61, s61, s60
	s_sub_i32 s8, s23, s61
	v_ashrrev_i32_e32 v14, 6, v12
	s_lshl_b32 s16, s8, 6
	v_cmp_gt_i32_e32 vcc, 64, v14
	s_and_saveexec_b64 s[20:21], vcc
	s_cbranch_execz .LBB0_65
	v_cmp_lt_i32_e32 vcc, -1, v6
	s_waitcnt lgkmcnt(0)
	v_lshl_add_u64 v[10:11], v[6:7], 2, s[18:19]
	v_mul_lo_u32 v6, v14, s86
	v_lshlrev_b32_e32 v13, 2, v13
	v_add3_u32 v6, v6, v13, 32
	s_mov_b64 s[18:19], 0
	v_mov_b32_e32 v200, 0
	v_mov_b32_e32 v201, 0
	v_mov_b32_e32 v202, 0
	v_mov_b32_e32 v203, 0
	v_mov_b32_e32 v204, 0
	v_mov_b32_e32 v205, 0
	v_mov_b32_e32 v206, 0
	v_mov_b32_e32 v207, 0
	v_mov_b32_e32 v216, 0
	v_mov_b32_e32 v217, 0
	v_mov_b32_e32 v218, 0
	v_mov_b32_e32 v219, 0
	v_mov_b32_e32 v220, 0
	v_mov_b32_e32 v221, 0
	v_mov_b32_e32 v222, 0
	v_mov_b32_e32 v223, 0
	s_and_saveexec_b64 s[8:9], vcc
	s_cbranch_execz .Lmy_xpa_store
	v_add_u32_e32 v13, s16, v14
	v_ashrrev_i32_e32 v15, 31, v13
	v_mul_lo_u32 v15, s12, v15
	v_mul_lo_u32 v30, s13, v13
	v_mad_u64_u32 v[16:17], s[60:61], s12, v13, 0
	v_add3_u32 v17, v17, v15, v30
	v_lshl_add_u64 v[16:17], v[16:17], 2, v[10:11]
	global_load_dword v200, v[16:17], off
	v_add_u32_e32 v14, 8, v14
	v_add_u32_e32 v13, s16, v14
	v_ashrrev_i32_e32 v15, 31, v13
	v_mul_lo_u32 v15, s12, v15
	v_mul_lo_u32 v30, s13, v13
	v_mad_u64_u32 v[16:17], s[60:61], s12, v13, 0
	v_add3_u32 v17, v17, v15, v30
	v_lshl_add_u64 v[16:17], v[16:17], 2, v[10:11]
	global_load_dword v201, v[16:17], off
	v_add_u32_e32 v14, 8, v14
	v_add_u32_e32 v13, s16, v14
	v_ashrrev_i32_e32 v15, 31, v13
	v_mul_lo_u32 v15, s12, v15
	v_mul_lo_u32 v30, s13, v13
	v_mad_u64_u32 v[16:17], s[60:61], s12, v13, 0
	v_add3_u32 v17, v17, v15, v30
	v_lshl_add_u64 v[16:17], v[16:17], 2, v[10:11]
	global_load_dword v202, v[16:17], off
	v_add_u32_e32 v14, 8, v14
	v_add_u32_e32 v13, s16, v14
	v_ashrrev_i32_e32 v15, 31, v13
	v_mul_lo_u32 v15, s12, v15
	v_mul_lo_u32 v30, s13, v13
	v_mad_u64_u32 v[16:17], s[60:61], s12, v13, 0
	v_add3_u32 v17, v17, v15, v30
	v_lshl_add_u64 v[16:17], v[16:17], 2, v[10:11]
	global_load_dword v203, v[16:17], off
	v_add_u32_e32 v14, 8, v14
	v_add_u32_e32 v13, s16, v14
	v_ashrrev_i32_e32 v15, 31, v13
	v_mul_lo_u32 v15, s12, v15
	v_mul_lo_u32 v30, s13, v13
	v_mad_u64_u32 v[16:17], s[60:61], s12, v13, 0
	v_add3_u32 v17, v17, v15, v30
	v_lshl_add_u64 v[16:17], v[16:17], 2, v[10:11]
	global_load_dword v204, v[16:17], off
	v_add_u32_e32 v14, 8, v14
	v_add_u32_e32 v13, s16, v14
	v_ashrrev_i32_e32 v15, 31, v13
	v_mul_lo_u32 v15, s12, v15
	v_mul_lo_u32 v30, s13, v13
	v_mad_u64_u32 v[16:17], s[60:61], s12, v13, 0
	v_add3_u32 v17, v17, v15, v30
	v_lshl_add_u64 v[16:17], v[16:17], 2, v[10:11]
	global_load_dword v205, v[16:17], off
	v_add_u32_e32 v14, 8, v14
	v_add_u32_e32 v13, s16, v14
	v_ashrrev_i32_e32 v15, 31, v13
	v_mul_lo_u32 v15, s12, v15
	v_mul_lo_u32 v30, s13, v13
	v_mad_u64_u32 v[16:17], s[60:61], s12, v13, 0
	v_add3_u32 v17, v17, v15, v30
	v_lshl_add_u64 v[16:17], v[16:17], 2, v[10:11]
	global_load_dword v206, v[16:17], off
	v_add_u32_e32 v14, 8, v14
	v_add_u32_e32 v13, s16, v14
	v_ashrrev_i32_e32 v15, 31, v13
	v_mul_lo_u32 v15, s12, v15
	v_mul_lo_u32 v30, s13, v13
	v_mad_u64_u32 v[16:17], s[60:61], s12, v13, 0
	v_add3_u32 v17, v17, v15, v30
	v_lshl_add_u64 v[16:17], v[16:17], 2, v[10:11]
	global_load_dword v207, v[16:17], off
	v_add_u32_e32 v14, 8, v14
	v_add_u32_e32 v13, s16, v14
	v_ashrrev_i32_e32 v15, 31, v13
	v_mul_lo_u32 v15, s12, v15
	v_mul_lo_u32 v30, s13, v13
	v_mad_u64_u32 v[16:17], s[60:61], s12, v13, 0
	v_add3_u32 v17, v17, v15, v30
	v_lshl_add_u64 v[16:17], v[16:17], 2, v[10:11]
	global_load_dword v216, v[16:17], off
	v_add_u32_e32 v14, 8, v14
	v_add_u32_e32 v13, s16, v14
	v_ashrrev_i32_e32 v15, 31, v13
	v_mul_lo_u32 v15, s12, v15
	v_mul_lo_u32 v30, s13, v13
	v_mad_u64_u32 v[16:17], s[60:61], s12, v13, 0
	v_add3_u32 v17, v17, v15, v30
	v_lshl_add_u64 v[16:17], v[16:17], 2, v[10:11]
	global_load_dword v217, v[16:17], off
	v_add_u32_e32 v14, 8, v14
	v_add_u32_e32 v13, s16, v14
	v_ashrrev_i32_e32 v15, 31, v13
	v_mul_lo_u32 v15, s12, v15
	v_mul_lo_u32 v30, s13, v13
	v_mad_u64_u32 v[16:17], s[60:61], s12, v13, 0
	v_add3_u32 v17, v17, v15, v30
	v_lshl_add_u64 v[16:17], v[16:17], 2, v[10:11]
	global_load_dword v218, v[16:17], off
	v_add_u32_e32 v14, 8, v14
	v_add_u32_e32 v13, s16, v14
	v_ashrrev_i32_e32 v15, 31, v13
	v_mul_lo_u32 v15, s12, v15
	v_mul_lo_u32 v30, s13, v13
	v_mad_u64_u32 v[16:17], s[60:61], s12, v13, 0
	v_add3_u32 v17, v17, v15, v30
	v_lshl_add_u64 v[16:17], v[16:17], 2, v[10:11]
	global_load_dword v219, v[16:17], off
	v_add_u32_e32 v14, 8, v14
	v_add_u32_e32 v13, s16, v14
	v_ashrrev_i32_e32 v15, 31, v13
	v_mul_lo_u32 v15, s12, v15
	v_mul_lo_u32 v30, s13, v13
	v_mad_u64_u32 v[16:17], s[60:61], s12, v13, 0
	v_add3_u32 v17, v17, v15, v30
	v_lshl_add_u64 v[16:17], v[16:17], 2, v[10:11]
	global_load_dword v220, v[16:17], off
	v_add_u32_e32 v14, 8, v14
	v_add_u32_e32 v13, s16, v14
	v_ashrrev_i32_e32 v15, 31, v13
	v_mul_lo_u32 v15, s12, v15
	v_mul_lo_u32 v30, s13, v13
	v_mad_u64_u32 v[16:17], s[60:61], s12, v13, 0
	v_add3_u32 v17, v17, v15, v30
	v_lshl_add_u64 v[16:17], v[16:17], 2, v[10:11]
	global_load_dword v221, v[16:17], off
	v_add_u32_e32 v14, 8, v14
	v_add_u32_e32 v13, s16, v14
	v_ashrrev_i32_e32 v15, 31, v13
	v_mul_lo_u32 v15, s12, v15
	v_mul_lo_u32 v30, s13, v13
	v_mad_u64_u32 v[16:17], s[60:61], s12, v13, 0
	v_add3_u32 v17, v17, v15, v30
	v_lshl_add_u64 v[16:17], v[16:17], 2, v[10:11]
	global_load_dword v222, v[16:17], off
	v_add_u32_e32 v14, 8, v14
	v_add_u32_e32 v13, s16, v14
	v_ashrrev_i32_e32 v15, 31, v13
	v_mul_lo_u32 v15, s12, v15
	v_mul_lo_u32 v30, s13, v13
	v_mad_u64_u32 v[16:17], s[60:61], s12, v13, 0
	v_add3_u32 v17, v17, v15, v30
	v_lshl_add_u64 v[16:17], v[16:17], 2, v[10:11]
	global_load_dword v223, v[16:17], off
.Lmy_xpa_store:
	s_or_b64 exec, exec, s[8:9]
	s_waitcnt vmcnt(0)
	ds_write_b32 v6, v200
	ds_write_b32 v6, v201 offset:2080
	ds_write_b32 v6, v202 offset:4160
	ds_write_b32 v6, v203 offset:6240
	ds_write_b32 v6, v204 offset:8320
	ds_write_b32 v6, v205 offset:10400
	ds_write_b32 v6, v206 offset:12480
	ds_write_b32 v6, v207 offset:14560
	ds_write_b32 v6, v216 offset:16640
	ds_write_b32 v6, v217 offset:18720
	ds_write_b32 v6, v218 offset:20800
	ds_write_b32 v6, v219 offset:22880
	ds_write_b32 v6, v220 offset:24960
	ds_write_b32 v6, v221 offset:27040
	ds_write_b32 v6, v222 offset:29120
	ds_write_b32 v6, v223 offset:31200
	s_branch .LBB0_65
